# P3 pass-1 GEMM K-loop: first iteration peeled with SrcC=0, 128 accumulator zeroing moves removed
# baseline (speedup 1.0000x reference)
; #define PG8_LAS __attribute__((address_space(3)))
; template <class Epi, class Sched, bool ALIGN_EPI = false, bool SP2 = false, bool HS = false>
; __device__ __forceinline__ void gemm_phase(PG8_LAS unsigned char* lds, const Gemm g, const Sched& S, const Epi& E) {
;     ...
;         const bool has_next = S.next(ui + 1, nxt);
;         const char* nA = has_next ? (const char*)g.A + (size_t)nxt.pm * tstep : cA; const char* nB = has_next ? (const char*)g.Bt + (size_t)nxt.pn * tstep : cB;
;         for (int t = 0; t < nt; t += 2) {
;             if constexpr (HS) {
;                 if (t == 4 || t == 8 || t == 12) {
;                     const PG8_LAS float* tab = (const PG8_LAS float*)(lds + 147456);
;                     const int hj = (t >> 2) - 1;
; #pragma unroll
;                     for (int a = 0; a < 2; ++a)
; #pragma unroll
;                         for (int m = 0; m < 4; ++m) {
;                             const float s = tab[(a * 128 + wr * 64 + m * 16 + fr) * 4 + hj];
; #pragma unroll
;                             for (int b = 0; b < 2; ++b)
; #pragma unroll
;                                 for (int n = 0; n < 2; ++n) acc[a][b][m][n] = acc[a][b][m][n] * s;
;                         }
;                 }
;             }
;             const bool last = (t == nt - 2);
;             const char* a1 = cA + (size_t)(t + 1) * kstep;
;             const char* a2 = last ? nA : cA + (size_t)(t + 2) * kstep; const char* b2 = last ? nB : cB + (size_t)(t + 2) * kstep;
;             const char* a3 = a2 + kstep; const char* b3 = b2 + kstep;
;             if (last && has_next) S.a_ready(nxt);
;             if constexpr (SP2) {
;             PG8_LDB(B0, 0, 0); PG8_LDB(B1, 0, 1); PG8_SCHED; PG8_LDA(At, 0, 0); PG8_STAGE(PG8_SA(1, 1), a1 + hstep, voffA);
;             PG8_WAIT_V(8); PG8_WAIT_L(0); PG8_BAR; PG8_MMA(0, 0, At, B0); PG8_MMA(0, 1, At, B1); PG8_BAR; PG8_SCHED;
;             PG8_LDA(At, 0, 1); PG8_STAGE(PG8_SB(0, 0), b2, voffB); PG8_STAGE(PG8_SB(0, 1), b2 + hstep, voffB); PG8_STAGE(PG8_SA(0, 0), a2, voffA);
;             PG8_WAIT_V(8); PG8_WAIT_L(0); PG8_BAR; PG8_MMA(1, 0, At, B0); PG8_MMA(1, 1, At, B1); PG8_BAR; PG8_SCHED;
;             PG8_LDB(B0, 1, 0); PG8_LDB(B1, 1, 1); PG8_SCHED; PG8_LDA(At, 1, 0); PG8_STAGE(PG8_SA(0, 1), a2 + hstep, voffA);
;             PG8_WAIT_V(8); PG8_WAIT_L(0); PG8_BAR; PG8_MMA(0, 0, At, B0); PG8_MMA(0, 1, At, B1); PG8_BAR; PG8_SCHED;
.LBB0_1931:
	s_add_i32 s84, s84, 1
	s_mov_b64 s[64:65], s[10:11]
	s_mul_i32 s10, s84, s72
	s_add_i32 s10, s10, s96
	s_cmpk_lt_i32 s10, 0x100
	s_cselect_b64 s[60:61], -1, 0
	s_lshl_b32 s11, s10, 3
	s_mov_b64 s[62:63], s[14:15]
	s_mov_b32 s15, s85
	s_mov_b32 s2, s85
	s_ashr_i32 s85, s10, 6
	s_and_b32 s11, s11, 56
	s_bfe_u32 s10, s10, 0x30003
	s_mov_b32 s14, s86
	s_mov_b32 s12, s86
	s_or_b32 s86, s11, s10
	s_and_b64 s[10:11], s[60:61], exec
	s_cselect_b32 s14, s86, s14
	s_cselect_b32 s10, s85, s15
	s_ashr_i32 s15, s14, 31
	s_lshl_b64 s[14:15], s[14:15], 19
	s_add_u32 s14, s46, s14
	s_addc_u32 s15, s47, s15
	s_and_b64 s[52:53], s[60:61], exec
	s_cselect_b32 s52, s15, s63
	s_cselect_b32 s53, s14, s62
	s_ashr_i32 s11, s10, 31
	s_lshl_b64 s[10:11], s[10:11], 19
	s_add_u32 s10, s0, s10
	s_addc_u32 s11, s1, s11
	s_and_b64 s[66:67], s[60:61], exec
	s_cselect_b32 s87, s11, s65
	s_cselect_b32 s88, s10, s64
	s_add_u32 s62, s62, 0x40080
	s_addc_u32 s63, s63, 0
	s_add_u32 s89, s64, 0x100
	s_addc_u32 s90, s65, 0
	s_mov_b32 s91, -2
	ds_read_b128 v[140:143], v152
	ds_read_b128 v[144:147], v152 offset:1024
	ds_read_b128 v[148:151], v152 offset:2048
	ds_read_b128 v[156:159], v152 offset:3072
	ds_read_b128 v[160:163], v153
	ds_read_b128 v[164:167], v153 offset:1024
	ds_read_b128 v[168:171], v153 offset:2048
	ds_read_b128 v[172:175], v153 offset:3072
	s_add_u32 s64, s62, 0xfffc0080
	s_addc_u32 s65, s63, -1
	s_cmp_eq_u32 s91, 12
	s_cselect_b32 s67, s52, s65
	s_cselect_b32 s66, s53, s64
	s_cselect_b32 s65, s87, s90
	s_cselect_b32 s64, s88, s89
	v_lshl_add_u64 v[184:185], s[62:63], 0, v[136:137]
	s_add_i32 m0, s7, 0xc000
	ds_read_b128 v[176:179], v154
	ds_read_b128 v[180:183], v154 offset:1024
	ds_read_b128 v[188:191], v154 offset:2048
	ds_read_b128 v[192:195], v154 offset:3072
	ds_read_b128 v[196:199], v154 offset:4096
	ds_read_b128 v[200:203], v154 offset:5120
	ds_read_b128 v[204:207], v154 offset:6144
	ds_read_b128 v[208:211], v154 offset:7168
	global_load_lds_dwordx4 v[184:185], off
	v_lshl_add_u64 v[184:185], s[62:63], 0, v[138:139]
	s_add_i32 m0, s7, 0xe000
	s_nop 0
	global_load_lds_dwordx4 v[184:185], off
	s_waitcnt vmcnt(8)
	s_waitcnt lgkmcnt(0)
	s_barrier
	s_setprio 1
	s_waitcnt lgkmcnt(0)
	v_mfma_f32_16x16x32_bf16 v[124:127], v[140:143], v[176:179], 0
	v_mfma_f32_16x16x32_bf16 v[120:123], v[148:151], v[176:179], 0
	v_mfma_f32_16x16x32_bf16 v[108:111], v[140:143], v[188:191], 0
	v_mfma_f32_16x16x32_bf16 v[104:107], v[148:151], v[188:191], 0
	v_mfma_f32_16x16x32_bf16 v[92:95], v[140:143], v[196:199], 0
	v_mfma_f32_16x16x32_bf16 v[88:91], v[148:151], v[196:199], 0
	v_mfma_f32_16x16x32_bf16 v[76:79], v[140:143], v[204:207], 0
	v_mfma_f32_16x16x32_bf16 v[72:75], v[148:151], v[204:207], 0
	v_mfma_f32_16x16x32_bf16 v[124:127], v[144:147], v[180:183], v[124:127]
	v_mfma_f32_16x16x32_bf16 v[120:123], v[156:159], v[180:183], v[120:123]
	v_mfma_f32_16x16x32_bf16 v[108:111], v[144:147], v[192:195], v[108:111]
	v_mfma_f32_16x16x32_bf16 v[104:107], v[156:159], v[192:195], v[104:107]
	v_mfma_f32_16x16x32_bf16 v[92:95], v[144:147], v[200:203], v[92:95]
	v_mfma_f32_16x16x32_bf16 v[88:91], v[156:159], v[200:203], v[88:91]
	v_mfma_f32_16x16x32_bf16 v[76:79], v[144:147], v[208:211], v[76:79]
	v_mfma_f32_16x16x32_bf16 v[72:75], v[156:159], v[208:211], v[72:75]
	s_setprio 0
	s_setprio 1
	v_mfma_f32_16x16x32_bf16 v[116:119], v[160:163], v[176:179], 0
	v_mfma_f32_16x16x32_bf16 v[112:115], v[168:171], v[176:179], 0
	v_mfma_f32_16x16x32_bf16 v[100:103], v[160:163], v[188:191], 0
	v_mfma_f32_16x16x32_bf16 v[96:99], v[168:171], v[188:191], 0
	v_mfma_f32_16x16x32_bf16 v[84:87], v[160:163], v[196:199], 0
	v_mfma_f32_16x16x32_bf16 v[80:83], v[168:171], v[196:199], 0
	v_mfma_f32_16x16x32_bf16 v[68:71], v[160:163], v[204:207], 0
	v_mfma_f32_16x16x32_bf16 v[64:67], v[168:171], v[204:207], 0
	v_mfma_f32_16x16x32_bf16 v[116:119], v[164:167], v[180:183], v[116:119]
	v_mfma_f32_16x16x32_bf16 v[112:115], v[172:175], v[180:183], v[112:115]
	v_mfma_f32_16x16x32_bf16 v[100:103], v[164:167], v[192:195], v[100:103]
	v_mfma_f32_16x16x32_bf16 v[96:99], v[172:175], v[192:195], v[96:99]
	v_mfma_f32_16x16x32_bf16 v[84:87], v[164:167], v[200:203], v[84:87]
	v_mfma_f32_16x16x32_bf16 v[80:83], v[172:175], v[200:203], v[80:83]
	v_mfma_f32_16x16x32_bf16 v[68:71], v[164:167], v[208:211], v[68:71]
	v_mfma_f32_16x16x32_bf16 v[64:67], v[172:175], v[208:211], v[64:67]
	s_setprio 0
	s_barrier
	s_add_i32 s92, s76, s3
	v_lshl_add_u64 v[184:185], s[64:65], 0, v[130:131]
	s_mov_b32 m0, s92
	ds_read_b128 v[176:179], v154 offset:16384
	ds_read_b128 v[180:183], v154 offset:17408
	ds_read_b128 v[188:191], v154 offset:18432
	ds_read_b128 v[192:195], v154 offset:19456
	ds_read_b128 v[196:199], v154 offset:20480
	ds_read_b128 v[200:203], v154 offset:21504
	ds_read_b128 v[204:207], v154 offset:22528
	ds_read_b128 v[208:211], v154 offset:23552
	global_load_lds_dwordx4 v[184:185], off
	s_add_i32 m0, s92, 0x2000
	s_add_u32 s92, s64, 0x40000
	v_lshl_add_u64 v[212:213], s[64:65], 0, v[128:129]
	s_addc_u32 s93, s65, 0
	s_add_i32 s94, s77, s3
	global_load_lds_dwordx4 v[212:213], off
	v_lshl_add_u64 v[214:215], s[92:93], 0, v[130:131]
	s_mov_b32 m0, s94
	v_lshl_add_u64 v[216:217], s[66:67], 0, v[128:129]
	global_load_lds_dwordx4 v[214:215], off
	v_lshl_add_u64 v[214:215], s[92:93], 0, v[128:129]
	s_add_i32 m0, s94, 0x2000
	s_nop 0
	global_load_lds_dwordx4 v[214:215], off
	v_lshl_add_u64 v[214:215], s[66:67], 0, v[130:131]
	s_mov_b32 m0, s7
	s_nop 0
	global_load_lds_dwordx4 v[214:215], off
	s_mov_b32 m0, s9
	s_nop 0
	global_load_lds_dwordx4 v[216:217], off
	s_waitcnt vmcnt(8)
	s_waitcnt lgkmcnt(0)
	s_barrier
; #define PG8_STAGE(bufoff, gbase, voff) do { _Pragma("unroll") for (int _i = 0; _i < 2; ++_i) \
;         __builtin_amdgcn_global_load_lds((const unsigned*)((const char*)(gbase) + (voff)[_i]), (PG8_LAS unsigned*)(lds + (bufoff) + ldsw + _i * 8192), 16, 0, 0); } while (0)
; #define PG8_LDA(dst, b, h) do { _Pragma("unroll") for (int m = 0; m < 4; ++m) _Pragma("unroll") for (int k = 0; k < 2; ++k) dst[m][k] = *(const PG8_LAS bf16x8*)(lds + PG8_SA(b, h) + aoff + m * 2048 + k * 1024); } while (0)
; #define PG8_LDB(dst, b, h) do { _Pragma("unroll") for (int n = 0; n < 2; ++n) _Pragma("unroll") for (int k = 0; k < 2; ++k) dst[n][k] = *(const PG8_LAS bf16x8*)(lds + PG8_SB(b, h) + boff + n * 2048 + k * 1024); } while (0)
; #define PG8_MMA(ai, bj, At, Bt) do { __builtin_amdgcn_s_setprio(1); _Pragma("unroll") for (int m = 0; m < 4; ++m) _Pragma("unroll") for (int n = 0; n < 2; ++n) _Pragma("unroll") for (int k = 0; k < 2; ++k) \
;         acc[ai][bj][m][n] = __builtin_amdgcn_mfma_f32_16x16x32_bf16(Bt[n][k], At[m][k], acc[ai][bj][m][n], 0, 0, 0); __builtin_amdgcn_s_setprio(0); } while (0)
; #define PG8_BAR __builtin_amdgcn_s_barrier()
; template <class Epi, class Sched, bool ALIGN_EPI = false, bool SP2 = false, bool HS = false>
; __device__ __forceinline__ void gemm_phase(PG8_LAS unsigned char* lds, const Gemm g, const Sched& S, const Epi& E) {
;     ...
;             PG8_LDB(B0, 0, 0); PG8_LDB(B1, 0, 1); PG8_SCHED; PG8_LDA(At, 0, 0); PG8_STAGE(PG8_SA(1, 1), a1 + hstep, voffA);
;             PG8_WAIT_V(8); PG8_WAIT_L(0); PG8_BAR; PG8_MMA(0, 0, At, B0); PG8_MMA(0, 1, At, B1); PG8_BAR; PG8_SCHED;
;             PG8_LDA(At, 0, 1); PG8_STAGE(PG8_SB(0, 0), b2, voffB); PG8_STAGE(PG8_SB(0, 1), b2 + hstep, voffB); PG8_STAGE(PG8_SA(0, 0), a2, voffA);
;             PG8_WAIT_V(8); PG8_WAIT_L(0); PG8_BAR; PG8_MMA(1, 0, At, B0); PG8_MMA(1, 1, At, B1); PG8_BAR; PG8_SCHED;
;             PG8_LDB(B0, 1, 0); PG8_LDB(B1, 1, 1); PG8_SCHED; PG8_LDA(At, 1, 0); PG8_STAGE(PG8_SA(0, 1), a2 + hstep, voffA);
;             PG8_WAIT_V(8); PG8_WAIT_L(0); PG8_BAR; PG8_MMA(0, 0, At, B0); PG8_MMA(0, 1, At, B1); PG8_BAR; PG8_SCHED;
;             PG8_LDA(At, 1, 1); PG8_STAGE(PG8_SB(1, 0), b3, voffB); PG8_STAGE(PG8_SB(1, 1), b3 + hstep, voffB); PG8_STAGE(PG8_SA(1, 0), a3, voffA);
;             PG8_WAIT_V(8); PG8_WAIT_L(0); PG8_BAR; PG8_MMA(1, 0, At, B0); PG8_MMA(1, 1, At, B1); PG8_BAR; PG8_SCHED;
	s_setprio 1
	s_waitcnt lgkmcnt(0)
	v_mfma_f32_16x16x32_bf16 v[60:63], v[140:143], v[176:179], 0
	v_mfma_f32_16x16x32_bf16 v[56:59], v[148:151], v[176:179], 0
	v_mfma_f32_16x16x32_bf16 v[44:47], v[140:143], v[188:191], 0
	v_mfma_f32_16x16x32_bf16 v[40:43], v[148:151], v[188:191], 0
	v_mfma_f32_16x16x32_bf16 v[28:31], v[140:143], v[196:199], 0
	v_mfma_f32_16x16x32_bf16 v[24:27], v[148:151], v[196:199], 0
	v_mfma_f32_16x16x32_bf16 v[16:19], v[140:143], v[204:207], 0
	v_mfma_f32_16x16x32_bf16 v[8:11], v[148:151], v[204:207], 0
	v_mfma_f32_16x16x32_bf16 v[60:63], v[144:147], v[180:183], v[60:63]
	v_mfma_f32_16x16x32_bf16 v[56:59], v[156:159], v[180:183], v[56:59]
	v_mfma_f32_16x16x32_bf16 v[44:47], v[144:147], v[192:195], v[44:47]
	v_mfma_f32_16x16x32_bf16 v[40:43], v[156:159], v[192:195], v[40:43]
	v_mfma_f32_16x16x32_bf16 v[28:31], v[144:147], v[200:203], v[28:31]
	v_mfma_f32_16x16x32_bf16 v[24:27], v[156:159], v[200:203], v[24:27]
	v_mfma_f32_16x16x32_bf16 v[16:19], v[144:147], v[208:211], v[16:19]
	v_mfma_f32_16x16x32_bf16 v[8:11], v[156:159], v[208:211], v[8:11]
	s_setprio 0
	s_setprio 1
	v_mfma_f32_16x16x32_bf16 v[52:55], v[160:163], v[176:179], 0
	v_mfma_f32_16x16x32_bf16 v[48:51], v[168:171], v[176:179], 0
	v_mfma_f32_16x16x32_bf16 v[36:39], v[160:163], v[188:191], 0
	v_mfma_f32_16x16x32_bf16 v[32:35], v[168:171], v[188:191], 0
	v_mfma_f32_16x16x32_bf16 v[20:23], v[160:163], v[196:199], 0
	v_mfma_f32_16x16x32_bf16 v[12:15], v[168:171], v[196:199], 0
	v_mfma_f32_16x16x32_bf16 v[4:7], v[160:163], v[204:207], 0
	v_mfma_f32_16x16x32_bf16 v[0:3], v[168:171], v[204:207], 0
	v_mfma_f32_16x16x32_bf16 v[52:55], v[164:167], v[180:183], v[52:55]
	v_mfma_f32_16x16x32_bf16 v[48:51], v[172:175], v[180:183], v[48:51]
	v_mfma_f32_16x16x32_bf16 v[36:39], v[164:167], v[192:195], v[36:39]
	v_mfma_f32_16x16x32_bf16 v[32:35], v[172:175], v[192:195], v[32:35]
	v_mfma_f32_16x16x32_bf16 v[20:23], v[164:167], v[200:203], v[20:23]
	v_mfma_f32_16x16x32_bf16 v[12:15], v[172:175], v[200:203], v[12:15]
	v_mfma_f32_16x16x32_bf16 v[4:7], v[164:167], v[208:211], v[4:7]
	v_mfma_f32_16x16x32_bf16 v[0:3], v[172:175], v[208:211], v[0:3]
	s_setprio 0
	s_barrier
	s_add_i32 s92, 0, 0x18000
	v_add_u32_e32 v155, s92, v133
	s_add_i32 s93, 0, 0x1c000
	ds_read_b128 v[140:143], v155
	ds_read_b128 v[144:147], v155 offset:1024
	ds_read_b128 v[148:151], v155 offset:2048
	ds_read_b128 v[156:159], v155 offset:3072
	v_add_u32_e32 v155, s93, v133
	ds_read_b128 v[160:163], v155
	ds_read_b128 v[164:167], v155 offset:1024
	ds_read_b128 v[168:171], v155 offset:2048
	ds_read_b128 v[172:175], v155 offset:3072
	s_add_u32 s66, s66, 0x40000
	s_addc_u32 s67, s67, 0
	s_mov_b32 m0, s25
	v_lshl_add_u64 v[218:219], s[66:67], 0, v[130:131]
	ds_read_b128 v[176:179], v154 offset:32768
	ds_read_b128 v[180:183], v154 offset:33792
	ds_read_b128 v[188:191], v154 offset:34816
	ds_read_b128 v[192:195], v154 offset:35840
	ds_read_b128 v[196:199], v154 offset:36864
	ds_read_b128 v[200:203], v154 offset:37888
	ds_read_b128 v[204:207], v154 offset:38912
	ds_read_b128 v[208:211], v154 offset:39936
	global_load_lds_dwordx4 v[218:219], off
	v_lshl_add_u64 v[218:219], s[66:67], 0, v[128:129]
	s_mov_b32 m0, s33
	s_nop 0
	global_load_lds_dwordx4 v[218:219], off
	s_waitcnt vmcnt(8)
	s_waitcnt lgkmcnt(0)
	s_barrier
	s_setprio 1
	s_waitcnt lgkmcnt(0)
	v_mfma_f32_16x16x32_bf16 v[124:127], v[140:143], v[176:179], v[124:127]
	v_mfma_f32_16x16x32_bf16 v[120:123], v[148:151], v[176:179], v[120:123]
	v_mfma_f32_16x16x32_bf16 v[108:111], v[140:143], v[188:191], v[108:111]
	v_mfma_f32_16x16x32_bf16 v[104:107], v[148:151], v[188:191], v[104:107]
	v_mfma_f32_16x16x32_bf16 v[92:95], v[140:143], v[196:199], v[92:95]
	v_mfma_f32_16x16x32_bf16 v[88:91], v[148:151], v[196:199], v[88:91]
	v_mfma_f32_16x16x32_bf16 v[76:79], v[140:143], v[204:207], v[76:79]
	v_mfma_f32_16x16x32_bf16 v[72:75], v[148:151], v[204:207], v[72:75]
	v_mfma_f32_16x16x32_bf16 v[124:127], v[144:147], v[180:183], v[124:127]
	v_mfma_f32_16x16x32_bf16 v[120:123], v[156:159], v[180:183], v[120:123]
	v_mfma_f32_16x16x32_bf16 v[108:111], v[144:147], v[192:195], v[108:111]
	v_mfma_f32_16x16x32_bf16 v[104:107], v[156:159], v[192:195], v[104:107]
	v_mfma_f32_16x16x32_bf16 v[92:95], v[144:147], v[200:203], v[92:95]
	v_mfma_f32_16x16x32_bf16 v[88:91], v[156:159], v[200:203], v[88:91]
	v_mfma_f32_16x16x32_bf16 v[76:79], v[144:147], v[208:211], v[76:79]
	v_mfma_f32_16x16x32_bf16 v[72:75], v[156:159], v[208:211], v[72:75]
	s_setprio 0
	s_setprio 1
	v_mfma_f32_16x16x32_bf16 v[116:119], v[160:163], v[176:179], v[116:119]
	v_mfma_f32_16x16x32_bf16 v[112:115], v[168:171], v[176:179], v[112:115]
	v_mfma_f32_16x16x32_bf16 v[100:103], v[160:163], v[188:191], v[100:103]
	v_mfma_f32_16x16x32_bf16 v[96:99], v[168:171], v[188:191], v[96:99]
	v_mfma_f32_16x16x32_bf16 v[84:87], v[160:163], v[196:199], v[84:87]
	v_mfma_f32_16x16x32_bf16 v[80:83], v[168:171], v[196:199], v[80:83]
	v_mfma_f32_16x16x32_bf16 v[68:71], v[160:163], v[204:207], v[68:71]
	v_mfma_f32_16x16x32_bf16 v[64:67], v[168:171], v[204:207], v[64:67]
	v_mfma_f32_16x16x32_bf16 v[116:119], v[164:167], v[180:183], v[116:119]
	v_mfma_f32_16x16x32_bf16 v[112:115], v[172:175], v[180:183], v[112:115]
	v_mfma_f32_16x16x32_bf16 v[100:103], v[164:167], v[192:195], v[100:103]
	v_mfma_f32_16x16x32_bf16 v[96:99], v[172:175], v[192:195], v[96:99]
	v_mfma_f32_16x16x32_bf16 v[84:87], v[164:167], v[200:203], v[84:87]
	v_mfma_f32_16x16x32_bf16 v[80:83], v[172:175], v[200:203], v[80:83]
	v_mfma_f32_16x16x32_bf16 v[68:71], v[164:167], v[208:211], v[68:71]
	v_mfma_f32_16x16x32_bf16 v[64:67], v[172:175], v[208:211], v[64:67]
	s_setprio 0
	s_barrier
; #define PG8_STAGE(bufoff, gbase, voff) do { _Pragma("unroll") for (int _i = 0; _i < 2; ++_i) \
;         __builtin_amdgcn_global_load_lds((const unsigned*)((const char*)(gbase) + (voff)[_i]), (PG8_LAS unsigned*)(lds + (bufoff) + ldsw + _i * 8192), 16, 0, 0); } while (0)
; #define PG8_LDA(dst, b, h) do { _Pragma("unroll") for (int m = 0; m < 4; ++m) _Pragma("unroll") for (int k = 0; k < 2; ++k) dst[m][k] = *(const PG8_LAS bf16x8*)(lds + PG8_SA(b, h) + aoff + m * 2048 + k * 1024); } while (0)
; #define PG8_MMA(ai, bj, At, Bt) do { __builtin_amdgcn_s_setprio(1); _Pragma("unroll") for (int m = 0; m < 4; ++m) _Pragma("unroll") for (int n = 0; n < 2; ++n) _Pragma("unroll") for (int k = 0; k < 2; ++k) \
;         acc[ai][bj][m][n] = __builtin_amdgcn_mfma_f32_16x16x32_bf16(Bt[n][k], At[m][k], acc[ai][bj][m][n], 0, 0, 0); __builtin_amdgcn_s_setprio(0); } while (0)
; #define PG8_WAIT_V(n) asm volatile("s_waitcnt vmcnt(" #n ")" ::: "memory")
; #define PG8_WAIT_L(n) asm volatile("s_waitcnt lgkmcnt(" #n ")" ::: "memory")
; #define PG8_BAR __builtin_amdgcn_s_barrier()
; #define PG8_SCHED __builtin_amdgcn_sched_barrier(0)
; template <class Epi, class Sched, bool ALIGN_EPI = false, bool SP2 = false, bool HS = false>
; __device__ __forceinline__ void gemm_phase(PG8_LAS unsigned char* lds, const Gemm g, const Sched& S, const Epi& E) {
;     ...
;         for (int t = 0; t < nt; t += 2) {
;     ...
;             PG8_LDA(At, 1, 1); PG8_STAGE(PG8_SB(1, 0), b3, voffB); PG8_STAGE(PG8_SB(1, 1), b3 + hstep, voffB); PG8_STAGE(PG8_SA(1, 0), a3, voffA);
;             PG8_WAIT_V(8); PG8_WAIT_L(0); PG8_BAR; PG8_MMA(1, 0, At, B0); PG8_MMA(1, 1, At, B1); PG8_BAR; PG8_SCHED;
	s_add_i32 s66, s92, s3
	v_lshl_add_u64 v[184:185], v[184:185], 0, s[18:19]
	s_mov_b32 m0, s66
	ds_read_b128 v[176:179], v154 offset:49152
	ds_read_b128 v[180:183], v154 offset:50176
	ds_read_b128 v[188:191], v154 offset:51200
	ds_read_b128 v[192:195], v154 offset:52224
	ds_read_b128 v[196:199], v154 offset:53248
	ds_read_b128 v[200:203], v154 offset:54272
	ds_read_b128 v[204:207], v154 offset:55296
	ds_read_b128 v[208:211], v154 offset:56320
	global_load_lds_dwordx4 v[184:185], off
	s_add_i32 m0, s66, 0x2000
	s_add_u32 s64, s64, 0x40080
	v_lshl_add_u64 v[184:185], v[212:213], 0, s[18:19]
	s_addc_u32 s65, s65, 0
	s_add_i32 s66, s93, s3
	global_load_lds_dwordx4 v[184:185], off
	v_lshl_add_u64 v[184:185], s[64:65], 0, v[130:131]
	s_mov_b32 m0, s66
	s_nop 0
	global_load_lds_dwordx4 v[184:185], off
	v_lshl_add_u64 v[184:185], s[64:65], 0, v[128:129]
	s_add_i32 m0, s66, 0x2000
	s_nop 0
	global_load_lds_dwordx4 v[184:185], off
	v_lshl_add_u64 v[184:185], v[214:215], 0, s[18:19]
	s_mov_b32 m0, s74
	s_nop 0
	global_load_lds_dwordx4 v[184:185], off
	v_lshl_add_u64 v[184:185], v[216:217], 0, s[18:19]
	s_mov_b32 m0, s75
	s_nop 0
	global_load_lds_dwordx4 v[184:185], off
	s_waitcnt vmcnt(8)
	s_waitcnt lgkmcnt(0)
	s_barrier
	s_setprio 1
	s_waitcnt lgkmcnt(0)
	v_mfma_f32_16x16x32_bf16 v[60:63], v[140:143], v[176:179], v[60:63]
	v_mfma_f32_16x16x32_bf16 v[56:59], v[148:151], v[176:179], v[56:59]
	v_mfma_f32_16x16x32_bf16 v[44:47], v[140:143], v[188:191], v[44:47]
	v_mfma_f32_16x16x32_bf16 v[40:43], v[148:151], v[188:191], v[40:43]
	v_mfma_f32_16x16x32_bf16 v[28:31], v[140:143], v[196:199], v[28:31]
	v_mfma_f32_16x16x32_bf16 v[24:27], v[148:151], v[196:199], v[24:27]
	v_mfma_f32_16x16x32_bf16 v[16:19], v[140:143], v[204:207], v[16:19]
	v_mfma_f32_16x16x32_bf16 v[8:11], v[148:151], v[204:207], v[8:11]
	v_mfma_f32_16x16x32_bf16 v[60:63], v[144:147], v[180:183], v[60:63]
	v_mfma_f32_16x16x32_bf16 v[56:59], v[156:159], v[180:183], v[56:59]
	v_mfma_f32_16x16x32_bf16 v[44:47], v[144:147], v[192:195], v[44:47]
	v_mfma_f32_16x16x32_bf16 v[40:43], v[156:159], v[192:195], v[40:43]
	v_mfma_f32_16x16x32_bf16 v[28:31], v[144:147], v[200:203], v[28:31]
	v_mfma_f32_16x16x32_bf16 v[24:27], v[156:159], v[200:203], v[24:27]
	v_mfma_f32_16x16x32_bf16 v[16:19], v[144:147], v[208:211], v[16:19]
	v_mfma_f32_16x16x32_bf16 v[8:11], v[156:159], v[208:211], v[8:11]
	s_setprio 0
	s_setprio 1
	v_mfma_f32_16x16x32_bf16 v[52:55], v[160:163], v[176:179], v[52:55]
	v_mfma_f32_16x16x32_bf16 v[48:51], v[168:171], v[176:179], v[48:51]
	v_mfma_f32_16x16x32_bf16 v[36:39], v[160:163], v[188:191], v[36:39]
	v_mfma_f32_16x16x32_bf16 v[32:35], v[168:171], v[188:191], v[32:35]
	v_mfma_f32_16x16x32_bf16 v[20:23], v[160:163], v[196:199], v[20:23]
	v_mfma_f32_16x16x32_bf16 v[12:15], v[168:171], v[196:199], v[12:15]
	v_mfma_f32_16x16x32_bf16 v[4:7], v[160:163], v[204:207], v[4:7]
	v_mfma_f32_16x16x32_bf16 v[0:3], v[168:171], v[204:207], v[0:3]
	v_mfma_f32_16x16x32_bf16 v[52:55], v[164:167], v[180:183], v[52:55]
	v_mfma_f32_16x16x32_bf16 v[48:51], v[172:175], v[180:183], v[48:51]
	v_mfma_f32_16x16x32_bf16 v[36:39], v[164:167], v[192:195], v[36:39]
	v_mfma_f32_16x16x32_bf16 v[32:35], v[172:175], v[192:195], v[32:35]
	v_mfma_f32_16x16x32_bf16 v[20:23], v[164:167], v[200:203], v[20:23]
	v_mfma_f32_16x16x32_bf16 v[12:15], v[172:175], v[200:203], v[12:15]
	v_mfma_f32_16x16x32_bf16 v[4:7], v[164:167], v[208:211], v[4:7]
	v_mfma_f32_16x16x32_bf16 v[0:3], v[172:175], v[208:211], v[0:3]
	s_setprio 0
	s_barrier
	s_add_i32 s91, s91, 2
	s_add_u32 s62, s62, 0x100
	s_addc_u32 s63, s63, 0
	s_add_u32 s89, s89, 0x100
	s_addc_u32 s90, s90, 0
	s_cmp_gt_u32 s91, 13
